# code placement: MLA attention loop body shifted +4 bytes (loop head now 8-byte aligned), rest of code parity unchanged
# speedup vs baseline: 1.0001x; 1.0001x over previous
; template <int DQK, int LDK> ...
;     ...
;   const int tid = tid_, wid = __builtin_amdgcn_readfirstlane(tid >> 6), lane = tid & 63, r32 = lane & 31, hi = lane >> 5;
;   char* QRw = lds + OFF_QR + wid * 4608;
;   bf16_t* V_lds = (bf16_t*)lds; bf16_t* K_lds = (bf16_t*)(lds + OFF_K); char* KR_lds = lds + OFF_KR;
;   float* ws = (float*)(lds + OFF_WS) + wid * 64; float* li_l = ws; float* al_l = ws + 32;
;   float m_reg = -1e30f, l_reg = 0; f32x16 o[4] = {}; bf16x8 qr[NQ];
;   const bf16_t* Qw = Qb + (long)(wid * QBLK + r32) * LDQ + hi * 8;
; #pragma unroll
;   for (int d0 = 0; d0 < NQ; ++d0) qr[d0] = *reinterpret_cast<const bf16x8*>(Qw + d0 * 16);
;   if constexpr (ROPE) {
;     const int pos = qpos0 + wid * QBLK + r32;
; #pragma unroll
;     for (int d = 0; d < 2; ++d) {
;       const float* cp = COS + pos * 32 + d * 16 + hi * 8; const float* sp = SIN + pos * 32 + d * 16 + hi * 8;
;       const f32x4 c0 = *(const f32x4*)cp, c1 = *(const f32x4*)(cp + 4), s0 = *(const f32x4*)sp, s1 = *(const f32x4*)(sp + 4);
;       const bf16x8 a = *reinterpret_cast<const bf16x8*>(Qw + (8 + d) * 16), b = *reinterpret_cast<const bf16x8*>(Qw + (10 + d) * 16);
;       float y1[8], y2[8];
; #pragma unroll
;       for (int e = 0; e < 8; ++e) { const float c = e < 4 ? c0[e & 3] : c1[e & 3], s = e < 4 ? s0[e & 3] : s1[e & 3];
;         const float x1 = __uint_as_float(((unsigned)(unsigned short)a[e]) << 16), x2 = __uint_as_float(((unsigned)(unsigned short)b[e]) << 16);
;         y1[e] = x1 * c - x2 * s; y2[e] = x2 * c + x1 * s; }
;       u32x4 wa = {pk2(y1[0], y1[1]), pk2(y1[2], y1[3]), pk2(y1[4], y1[5]), pk2(y1[6], y1[7])};
;       u32x4 wb = {pk2(y2[0], y2[1]), pk2(y2[2], y2[3]), pk2(y2[4], y2[5]), pk2(y2[6], y2[7])};
; __global__ void __launch_bounds__(512) fwd_mega(Args a_kernarg) {
;     ...
;                     int rowbase, seq, qb, h;
;                     if (uu < 512) { qb = uu & 31; h = (uu >> 5) & 7; rowbase = HTOK + (uu >> 8) * 8192; seq = 8192; }
;                     else { const int u = uu - 512; qb = u & 7; h = (u >> 3) & 7; rowbase = (u >> 6) * 2048; seq = 2048; }
;                     const bf16_t* Kh = KV + (size_t)rowbase * 2048 + h * 256;
;     ...
;                     att::attn_unit<192, 2048>(Q + (size_t)(rowbase + qb * 256) * 1536 + h * 192, Kh, Kh + 128, KR + (size_t)rowbase * 64,
.LBB0_342:
	s_lshl_b32 s2, s7, 5
	s_cmpk_lt_i32 s7, 0x200
	s_cselect_b32 s5, 0xffffe000, s71
	s_movk_i32 s8, 0x4000
	s_cselect_b32 s3, 31, 7
	s_cselect_b32 s4, 5, 3
	s_cselect_b32 s8, s8, 0xffffc000
	s_cselect_b32 s15, 0x80, 32
	s_and_b32 s2, s2, s5
	s_and_b32 s14, s7, s3
	s_lshr_b32 s3, s7, s4
	s_add_i32 s2, s2, s8
	s_and_b32 s9, s3, 7
	s_ashr_i32 s3, s2, 31
	s_lshl_b64 s[4:5], s[2:3], 12
	v_readlane_b32 s16, v252, 29
	v_readlane_b32 s17, v252, 30
	s_add_u32 s4, s16, s4
	s_addc_u32 s5, s17, s5
	s_lshl_b32 s20, s9, 9
	s_add_u32 s16, s4, s20
	s_addc_u32 s17, s5, 0
	s_lshl_b32 s14, s14, 8
	s_add_i32 s34, s14, s2
	s_ashr_i32 s35, s34, 31
	s_mul_i32 s5, s34, 0xc00
	s_mul_hi_i32 s4, s34, 0xc00
	s_add_u32 s5, s56, s5
	s_addc_u32 s4, s57, s4
	s_mul_i32 s8, s9, 0x180
	s_add_u32 s28, s5, s8
	s_addc_u32 s29, s4, 0
	s_lshl_b64 s[4:5], s[2:3], 7
	v_readlane_b32 s8, v252, 39
	s_waitcnt vmcnt(0)
	v_mov_b32_e32 v56, v200
	s_add_u32 s18, s8, s4
	v_readlane_b32 s8, v252, 40
	s_addc_u32 s19, s8, s5
	v_readfirstlane_b32 s21, v56
	s_ashr_i32 s8, s21, 6
	v_and_b32_e32 v176, 31, v56
	s_lshl_b32 s26, s8, 5
	s_waitcnt vmcnt(4)
	v_or_b32_e32 v10, s14, v176
	v_add_lshl_u32 v10, v10, s26, 5
	v_ashrrev_i32_e32 v11, 31, v10
	v_readlane_b32 s24, v252, 3
	v_bfe_u32 v177, v56, 5, 1
	v_or_b32_e32 v0, s26, v176
	v_mov_b64_e32 v[2:3], s[28:29]
	v_lshlrev_b64 v[10:11], 2, v[10:11]
	v_readlane_b32 s25, v252, 4
	v_mad_i64_i32 v[2:3], s[28:29], v0, s23, v[2:3]
	v_lshlrev_b32_e32 v0, 4, v177
	v_lshl_add_u64 v[12:13], s[24:25], 0, v[10:11]
	v_readlane_b32 s24, v252, 5
	v_lshl_add_u64 v[50:51], v[2:3], 0, v[0:1]
	v_readlane_b32 s25, v252, 6
	global_load_dwordx4 v[2:5], v[50:51], off offset:256
	global_load_dwordx4 v[6:9], v[50:51], off offset:320
	s_waitcnt vmcnt(2)
	v_and_b32_e32 v14, 32, v56
	v_mov_b32_e32 v15, v1
	v_lshl_add_u64 v[10:11], s[24:25], 0, v[10:11]
	v_lshl_add_u64 v[46:47], v[10:11], 0, v[14:15]
	v_lshl_add_u64 v[38:39], v[12:13], 0, v[14:15]
	global_load_dwordx4 v[10:13], v[46:47], off
	global_load_dwordx4 v[14:17], v[38:39], off
	global_load_dwordx4 v[18:21], v[46:47], off offset:16
	global_load_dwordx4 v[22:25], v[38:39], off offset:16
	global_load_dwordx4 v[142:145], v[50:51], off
	global_load_dwordx4 v[134:137], v[50:51], off offset:32
	global_load_dwordx4 v[26:29], v[50:51], off offset:288
	global_load_dwordx4 v[30:33], v[50:51], off offset:352
	global_load_dwordx4 v[34:37], v[38:39], off offset:80
	s_nop 0
	global_load_dwordx4 v[38:41], v[38:39], off offset:64
	s_nop 0
	global_load_dwordx4 v[42:45], v[46:47], off offset:80
	s_nop 0
	global_load_dwordx4 v[46:49], v[46:47], off offset:64
	s_nop 0
	global_load_dwordx4 v[158:161], v[50:51], off offset:64
	global_load_dwordx4 v[154:157], v[50:51], off offset:96
	global_load_dwordx4 v[150:153], v[50:51], off offset:128
	global_load_dwordx4 v[146:149], v[50:51], off offset:160
	global_load_dwordx4 v[138:141], v[50:51], off offset:192
	global_load_dwordx4 v[130:133], v[50:51], off offset:224
	s_and_b32 s14, s21, 0x3fffffc0
	s_mul_i32 s21, s8, 0x1200
	s_add_i32 s21, s21, 0
	v_mul_u32_u24_e32 v57, 0x90, v176
	s_add_i32 s21, s21, 0x15800
	v_mov_b32_e32 v67, v1
	s_lshl_b32 s14, s14, 2
	s_add_i32 s14, s14, 0
	s_add_i32 s14, s14, 0x15000
	s_cmp_lg_u32 0, -1
	v_or_b32_e32 v83, 32, v0
	v_and_b32_e32 v178, 63, v56
	v_mad_u32_u24 v192, v176, s74, v83
	s_mov_b64 s[28:29], 0x40000
	s_mov_b64 s[24:25], 0x60000
	s_mov_b32 s76, s77
	s_mov_b32 s78, s77
	s_mov_b32 s79, s77
	s_mov_b32 s80, s77
	s_mov_b32 s81, s77
	s_mov_b32 s82, s77
	s_mov_b32 s83, s77
	s_mov_b32 s84, s77
	s_mov_b32 s85, s77
	s_mov_b32 s86, s77
	s_mov_b32 s87, s77
	s_mov_b32 s88, s77
	s_mov_b32 s89, s77
	s_mov_b32 s90, s77
	s_mov_b32 s91, s77
	v_cmp_gt_u32_e64 s[40:41], 32, v178
	v_lshl_add_u32 v179, v176, 2, s14
	v_mov_b32_e32 v180, 0
	s_waitcnt vmcnt(19)
	v_and_b32_e32 v51, 0xffff0000, v2
	v_lshlrev_b32_e32 v50, 16, v2
	v_and_b32_e32 v55, 0xffff0000, v3
	v_lshlrev_b32_e32 v54, 16, v3
	s_waitcnt vmcnt(18)
	v_and_b32_e32 v3, 0xffff0000, v7
	v_lshlrev_b32_e32 v2, 16, v7
	v_and_b32_e32 v59, 0xffff0000, v8
	v_lshlrev_b32_e32 v58, 16, v8
	s_waitcnt vmcnt(17)
	v_pk_mul_f32 v[62:63], v[12:13], v[2:3]
	s_waitcnt vmcnt(16)
	v_pk_mul_f32 v[2:3], v[16:17], v[2:3]
	v_and_b32_e32 v53, 0xffff0000, v6
	v_lshlrev_b32_e32 v52, 16, v6
	v_and_b32_e32 v7, 0xffff0000, v4
	v_lshlrev_b32_e32 v6, 16, v4
	s_waitcnt vmcnt(15)
	v_pk_mul_f32 v[64:65], v[18:19], v[58:59]
	s_waitcnt vmcnt(14)
	v_pk_mul_f32 v[58:59], v[22:23], v[58:59]
	v_pk_fma_f32 v[12:13], v[12:13], v[54:55], v[2:3]
	v_and_b32_e32 v3, 0xffff0000, v5
	v_lshlrev_b32_e32 v2, 16, v5
	v_and_b32_e32 v5, 0xffff0000, v9
	v_lshlrev_b32_e32 v4, 16, v9
	v_pk_mul_f32 v[60:61], v[10:11], v[52:53]
	v_pk_mul_f32 v[52:53], v[14:15], v[52:53]
	v_pk_fma_f32 v[22:23], v[22:23], v[6:7], v[64:65] neg_lo:[0,0,1] neg_hi:[0,0,1]
	v_pk_fma_f32 v[18:19], v[18:19], v[6:7], v[58:59]
	v_pk_mul_f32 v[6:7], v[20:21], v[4:5]
	v_pk_fma_f32 v[14:15], v[14:15], v[50:51], v[60:61] neg_lo:[0,0,1] neg_hi:[0,0,1]
	v_pk_fma_f32 v[10:11], v[10:11], v[50:51], v[52:53]
	v_pk_fma_f32 v[16:17], v[16:17], v[54:55], v[62:63] neg_lo:[0,0,1] neg_hi:[0,0,1]
	v_pk_fma_f32 v[6:7], v[24:25], v[2:3], v[6:7] neg_lo:[0,0,1] neg_hi:[0,0,1]
	v_pk_mul_f32 v[4:5], v[24:25], v[4:5]
	v_ashrrev_i32_e32 v50, 4, v56
	v_pk_fma_f32 v[20:21], v[20:21], v[2:3], v[4:5]
	v_cvt_pk_bf16_f32 v2, v14, v15
	v_cvt_pk_bf16_f32 v3, v16, v17
	v_cvt_pk_bf16_f32 v4, v22, v23
	v_cvt_pk_bf16_f32 v5, v6, v7
	v_add3_u32 v55, s21, v57, v0
	v_lshlrev_b32_e32 v57, 3, v56
	v_add_u32_e32 v62, 32, v50
	ds_write_b128 v55, v[2:5]
	v_and_b32_e32 v2, 0x78, v57
	v_ashrrev_i32_e32 v51, 31, v50
	v_ashrrev_i32_e32 v63, 31, v62
	v_lshlrev_b32_e32 v54, 1, v2
	v_ashrrev_i32_e32 v64, 3, v56
	v_lshlrev_b64 v[2:3], 12, v[50:51]
	v_lshlrev_b64 v[4:5], 12, v[62:63]
	v_or_b32_e32 v2, v2, v54
	v_or_b32_e32 v4, v4, v54
	v_ashrrev_i32_e32 v65, 31, v64
	v_lshl_add_u64 v[2:3], s[16:17], 0, v[2:3]
	v_lshl_add_u64 v[4:5], s[16:17], 0, v[4:5]
	v_and_b32_e32 v166, 56, v57
	v_lshlrev_b64 v[52:53], 7, v[64:65]
	v_cvt_pk_bf16_f32 v6, v10, v11
	v_cvt_pk_bf16_f32 v7, v12, v13
	v_cvt_pk_bf16_f32 v8, v18, v19
	v_cvt_pk_bf16_f32 v9, v20, v21
	global_load_dwordx4 v[10:13], v[2:3], off offset:256
	global_load_dwordx4 v[14:17], v[4:5], off offset:256
	global_load_dwordx4 v[18:21], v[2:3], off
	global_load_dwordx4 v[22:25], v[4:5], off
	v_lshl_add_u64 v[4:5], s[18:19], 0, v[52:53]
	v_lshlrev_b32_e32 v66, 1, v166
	v_lshl_add_u64 v[4:5], v[4:5], 0, v[66:67]
	global_load_dwordx4 v[58:61], v[4:5], off
	ds_write_b128 v55, v[6:9] offset:64
	s_waitcnt vmcnt(15)
; __device__ __forceinline__ unsigned pk2(float lo, float hi) { f32x2_t v = {lo, hi}; bf16x2_t b = __builtin_convertvector(v, bf16x2_t); return __builtin_bit_cast(unsigned, b); }
; __device__ __forceinline__ int v_st(int k, int c) { const int kk = (k & ~0xC) | ((k & 4) << 1) | ((k & 8) >> 1); return ((kk >> 3) * 4 + (c >> 5)) * 512 + ((kk & 7) * 32 + (c & 31)) * 2; }
; template <int DQK, int LDK> ...
;     ...
;   if constexpr (ROPE) {
;     const int pos = qpos0 + wid * QBLK + r32;
; #pragma unroll
;     for (int d = 0; d < 2; ++d) {
;       const float* cp = COS + pos * 32 + d * 16 + hi * 8; const float* sp = SIN + pos * 32 + d * 16 + hi * 8;
;       const f32x4 c0 = *(const f32x4*)cp, c1 = *(const f32x4*)(cp + 4), s0 = *(const f32x4*)sp, s1 = *(const f32x4*)(sp + 4);
;       const bf16x8 a = *reinterpret_cast<const bf16x8*>(Qw + (8 + d) * 16), b = *reinterpret_cast<const bf16x8*>(Qw + (10 + d) * 16);
;       float y1[8], y2[8];
; #pragma unroll
;       for (int e = 0; e < 8; ++e) { const float c = e < 4 ? c0[e & 3] : c1[e & 3], s = e < 4 ? s0[e & 3] : s1[e & 3];
;         const float x1 = __uint_as_float(((unsigned)(unsigned short)a[e]) << 16), x2 = __uint_as_float(((unsigned)(unsigned short)b[e]) << 16);
;         y1[e] = x1 * c - x2 * s; y2[e] = x2 * c + x1 * s; }
;       u32x4 wa = {pk2(y1[0], y1[1]), pk2(y1[2], y1[3]), pk2(y1[4], y1[5]), pk2(y1[6], y1[7])};
;       u32x4 wb = {pk2(y2[0], y2[1]), pk2(y2[2], y2[3]), pk2(y2[4], y2[5]), pk2(y2[6], y2[7])};
;       *(u32x4*)(QRw + KRSWZ(r32, (d * 16 + hi * 8) * 2)) = wa; *(u32x4*)(QRw + KRSWZ(r32, (32 + d * 16 + hi * 8) * 2)) = wb;
;     }
;   }
;   const int sr = tid >> 4, sc = (tid & 15) * 8, vst0 = v_st(sr, sc), vst1 = v_st(32 + sr, sc);
;   const int krr = tid >> 3, krc = (tid & 7) * 8;
;   const int vb0 = (int)(uintptr_t)V_lds + v_rd_base(lane);
;   constexpr int SD = ROPE ? 1 : 2;
;   struct { bf16x8 vs0, vs1, ks0, ks1, kr; } sr_[SD];
;     ...
;   f32x16 pA0, pA1, pB0, pB1; float mnA, mnB, alA, alB; bf16x8 pa0, pa1, pa2, pa3; const int NT = seq / KVBLK;
;   constexpr int SE = 0, SO = SD - 1;
;   SLOAD(SE, 0); asm volatile("s_waitcnt vmcnt(0)" ::: "memory"); SWRITE(0, SE); __syncthreads();
;   qkt<DQK>(pA0, pA1, K_lds, KR_lds, QRw, qr, r32, hi); partialSM<DQK>(pA0, pA1, m_reg, mnA, alA);
	v_and_b32_e32 v9, 0xffff0000, v30
	v_lshlrev_b32_e32 v8, 16, v30
	v_and_b32_e32 v7, 0xffff0000, v26
	v_lshlrev_b32_e32 v6, 16, v26
	s_waitcnt vmcnt(11)
	v_pk_mul_f32 v[68:69], v[46:47], v[8:9]
	v_pk_mul_f32 v[8:9], v[38:39], v[8:9]
	v_pk_fma_f32 v[68:69], v[38:39], v[6:7], v[68:69] neg_lo:[0,0,1] neg_hi:[0,0,1]
	v_pk_fma_f32 v[38:39], v[46:47], v[6:7], v[8:9]
	v_and_b32_e32 v9, 0xffff0000, v31
	v_lshlrev_b32_e32 v8, 16, v31
	v_and_b32_e32 v7, 0xffff0000, v27
	v_lshlrev_b32_e32 v6, 16, v27
	v_pk_mul_f32 v[26:27], v[48:49], v[8:9]
	v_pk_mul_f32 v[8:9], v[40:41], v[8:9]
	v_pk_fma_f32 v[26:27], v[40:41], v[6:7], v[26:27] neg_lo:[0,0,1] neg_hi:[0,0,1]
	v_pk_fma_f32 v[30:31], v[48:49], v[6:7], v[8:9]
	v_and_b32_e32 v9, 0xffff0000, v32
	v_lshlrev_b32_e32 v8, 16, v32
	v_and_b32_e32 v7, 0xffff0000, v28
	v_lshlrev_b32_e32 v6, 16, v28
	v_pk_mul_f32 v[40:41], v[42:43], v[8:9]
	v_pk_mul_f32 v[8:9], v[34:35], v[8:9]
	v_pk_fma_f32 v[40:41], v[34:35], v[6:7], v[40:41] neg_lo:[0,0,1] neg_hi:[0,0,1]
	v_pk_fma_f32 v[34:35], v[42:43], v[6:7], v[8:9]
	v_and_b32_e32 v9, 0xffff0000, v33
	v_lshlrev_b32_e32 v8, 16, v33
	v_and_b32_e32 v7, 0xffff0000, v29
	v_lshlrev_b32_e32 v6, 16, v29
	v_pk_mul_f32 v[28:29], v[44:45], v[8:9]
	v_pk_mul_f32 v[8:9], v[36:37], v[8:9]
	v_pk_fma_f32 v[28:29], v[36:37], v[6:7], v[28:29] neg_lo:[0,0,1] neg_hi:[0,0,1]
	v_pk_fma_f32 v[32:33], v[44:45], v[6:7], v[8:9]
	v_cvt_pk_bf16_f32 v6, v68, v69
	v_cvt_pk_bf16_f32 v7, v26, v27
	v_cvt_pk_bf16_f32 v8, v40, v41
	v_cvt_pk_bf16_f32 v9, v28, v29
	v_cvt_pk_bf16_f32 v26, v38, v39
	v_cvt_pk_bf16_f32 v27, v30, v31
	v_cvt_pk_bf16_f32 v28, v34, v35
	v_cvt_pk_bf16_f32 v29, v32, v33
	ds_write_b128 v55, v[6:9] offset:32
	ds_write_b128 v55, v[26:29] offset:96
	v_and_b32_e32 v6, 0xfffff0, v50
	v_lshlrev_b32_e32 v7, 1, v50
	v_and_b32_e32 v26, 0xfffff0, v62
	v_lshlrev_b32_e32 v27, 1, v62
	v_and_or_b32 v6, v7, 8, v6
	v_and_or_b32 v26, v27, 8, v26
	v_lshrrev_b32_e32 v7, 1, v50
	v_lshrrev_b32_e32 v6, 1, v6
	v_bfe_u32 v8, v57, 5, 2
	v_and_b32_e32 v9, 3, v50
	v_lshrrev_b32_e32 v26, 1, v26
	v_or_b32_e32 v6, v6, v8
	v_and_or_b32 v7, v7, 4, v9
	v_or_b32_e32 v8, v26, v8
	v_lshlrev_b32_e32 v6, 9, v6
	v_lshlrev_b32_e32 v7, 6, v7
	v_and_b32_e32 v9, 48, v54
	v_lshlrev_b32_e32 v8, 9, v8
	v_or3_b32 v6, v6, v7, v9
	v_or3_b32 v7, v8, v7, v9
	v_add_u32_e32 v185, 0, v6
	v_add_u32_e32 v186, 0, v7
	v_mad_u64_u32 v[6:7], s[18:19], v50, s75, v[54:55]
	v_mad_u64_u32 v[54:55], s[18:19], v64, s74, v[66:67]
	s_cselect_b32 s17, 0, 0
	s_add_i32 s18, 0, 0x10800
	v_mad_u32_u24 v55, v176, s75, v0
	v_add_u32_e32 v187, 0, v6
	v_add_u32_e32 v6, s18, v54
	v_add_u32_e32 v183, 0, v55
	s_waitcnt vmcnt(0)
	s_waitcnt vmcnt(4)
	ds_write_b128 v185, v[10:13]
	s_waitcnt vmcnt(3)
	ds_write_b128 v186, v[14:17]
	s_waitcnt vmcnt(2)
	ds_write_b128 v187, v[18:21] offset:32768
	s_waitcnt vmcnt(1)
	ds_write_b128 v187, v[22:25] offset:41472
	v_lshlrev_b32_e32 v57, 3, v178
	s_waitcnt vmcnt(0)
	ds_write_b128 v6, v[58:61]
	s_waitcnt lgkmcnt(0)
	s_barrier
	ds_read_b128 v[6:9], v183 offset:32768
	ds_read_b128 v[10:13], v183 offset:32800
	s_waitcnt lgkmcnt(1)
	v_mfma_f32_32x32x16_bf16 v[18:33], v[6:9], v[142:145], 0
	ds_read_b128 v[6:9], v183 offset:41472
	ds_read_b128 v[14:17], v183 offset:41504
	v_add_u32_e32 v193, s18, v192
	s_mov_b32 s19, 0x40000
	v_add_u32_e32 v218, 0, v54
	v_add_u32_e32 v219, 0x12c00, v218
	v_lshl_add_u64 v[168:169], v[52:53], 0, s[4:5]
	s_mov_b32 s16, 2
	s_waitcnt lgkmcnt(1)
	v_mfma_f32_32x32x16_bf16 v[34:49], v[6:9], v[142:145], 0
	v_mfma_f32_32x32x16_bf16 v[18:33], v[10:13], v[134:137], v[18:33]
	ds_read_b128 v[6:9], v183 offset:32832
	ds_read_b128 v[10:13], v183 offset:32864
	s_waitcnt lgkmcnt(2)
	v_mfma_f32_32x32x16_bf16 v[34:49], v[14:17], v[134:137], v[34:49]
	s_waitcnt lgkmcnt(1)
	v_mfma_f32_32x32x16_bf16 v[18:33], v[6:9], v[158:161], v[18:33]
	ds_read_b128 v[6:9], v183 offset:41536
	ds_read_b128 v[14:17], v183 offset:41568
	s_waitcnt lgkmcnt(1)
	v_mfma_f32_32x32x16_bf16 v[34:49], v[6:9], v[158:161], v[34:49]
	v_mfma_f32_32x32x16_bf16 v[18:33], v[10:13], v[154:157], v[18:33]
	ds_read_b128 v[6:9], v183 offset:32896
	ds_read_b128 v[10:13], v183 offset:32928
	s_waitcnt lgkmcnt(2)
	v_mfma_f32_32x32x16_bf16 v[34:49], v[14:17], v[154:157], v[34:49]
	s_waitcnt lgkmcnt(1)
	v_mfma_f32_32x32x16_bf16 v[18:33], v[6:9], v[150:153], v[18:33]
	ds_read_b128 v[6:9], v183 offset:41600
	ds_read_b128 v[14:17], v183 offset:41632
	s_waitcnt lgkmcnt(1)
	v_mfma_f32_32x32x16_bf16 v[34:49], v[6:9], v[150:153], v[34:49]
	v_mfma_f32_32x32x16_bf16 v[18:33], v[10:13], v[146:149], v[18:33]
	ds_read_b128 v[6:9], v183 offset:32960
	ds_read_b128 v[10:13], v183 offset:32992
	s_waitcnt lgkmcnt(2)
	v_mfma_f32_32x32x16_bf16 v[34:49], v[14:17], v[146:149], v[34:49]
	s_waitcnt lgkmcnt(1)
	v_mfma_f32_32x32x16_bf16 v[18:33], v[6:9], v[138:141], v[18:33]
	ds_read_b128 v[6:9], v183 offset:41664
	ds_read_b128 v[14:17], v183 offset:41696
	s_waitcnt lgkmcnt(1)
	v_mfma_f32_32x32x16_bf16 v[34:49], v[6:9], v[138:141], v[34:49]
	v_lshlrev_b32_e32 v6, 7, v176
	v_sub_u32_e32 v188, v55, v6
	v_add_u32_e32 v189, s18, v188
	ds_read_b128 v[6:9], v189
	v_mad_u32_u24 v55, v176, s74, v204
	v_add_u32_e32 v184, s21, v188
	v_add_u32_e32 v190, v55, v0
	v_mfma_f32_32x32x16_bf16 v[18:33], v[10:13], v[130:133], v[18:33]
	ds_read_b128 v[10:13], v184
	v_add_u32_e32 v191, s18, v190
	v_add_u32_e32 v198, v83, v55
	v_add_u32_e32 v199, s18, v198
	s_mov_b32 s21, 0x42ddb3d8
	s_waitcnt lgkmcnt(2)
	v_mfma_f32_32x32x16_bf16 v[34:49], v[14:17], v[130:133], v[34:49]
	ds_read_b128 v[14:17], v191
	ds_read_b128 v[58:61], v184 offset:32
	s_waitcnt lgkmcnt(2)
; #define SWAIT() do { if constexpr (SD == 1) asm volatile("s_waitcnt vmcnt(0)" ::: "memory"); else asm volatile("s_waitcnt vmcnt(4)" ::: "memory"); } while (0)
; template <int DQK> __device__ __forceinline__ void partialSM(f32x16& p0, f32x16& p1, float& m_reg, float& mn, float& alpha) {
;   constexpr float SCALE = (DQK == 192) ? 0.07216878364870322f : (DQK == 64 ? 1.0f : 0.08838834764831845f);
;   constexpr float C = SCALE * 1.4426950408889634f;
;   float pmax = p0[0];
; #pragma unroll
;   for (int r = 1; r < 16; ++r) pmax = fmaxf(pmax, p0[r]);
; #pragma unroll
;   for (int r = 0; r < 16; ++r) pmax = fmaxf(pmax, p1[r]);
;   { auto rr = __builtin_amdgcn_permlane32_swap(__float_as_uint(pmax), __float_as_uint(pmax), false, false);
;     pmax = fmaxf(__uint_as_float(rr[0]), __uint_as_float(rr[1])); }
;   if (__builtin_expect(__all(pmax - m_reg <= THR / SCALE), 1)) { mn = m_reg; alpha = 1.f; }
;   else { mn = fmaxf(m_reg, pmax); alpha = __builtin_amdgcn_exp2f((m_reg - mn) * C); m_reg = mn; }
;   float mnC = -mn * C;
; #pragma unroll
;   for (int r = 0; r < 16; ++r) p0[r] = fmaf(p0[r], C, mnC);
; #pragma unroll
;   for (int r = 0; r < 16; ++r) p1[r] = fmaf(p1[r], C, mnC);
; #pragma unroll
;   for (int r = 0; r < 16; ++r) p0[r] = __builtin_amdgcn_exp2f(p0[r]);
; }
; template <int DQK, int LDK> ...
;     ...
;   qkt<DQK>(pA0, pA1, K_lds, KR_lds, QRw, qr, r32, hi); partialSM<DQK>(pA0, pA1, m_reg, mnA, alA);
;   SLOAD(SO, KVBLK); if constexpr (SD == 2) { if (2 < NT) SLOAD(SE, 2 * KVBLK); }
;   SWAIT(); SWRITE(1, SO); __syncthreads();
	v_mfma_f32_32x32x16_bf16 v[18:33], v[6:9], v[10:13], v[18:33]
	v_lshlrev_b32_e32 v6, 4, v56
	v_and_b32_e32 v6, 0xc0, v6
	v_and_or_b32 v82, v57, 24, v6
	ds_read_b128 v[6:9], v193
	s_waitcnt lgkmcnt(2)
	v_mfma_f32_32x32x16_bf16 v[34:49], v[14:17], v[10:13], v[34:49]
	v_lshl_add_u64 v[10:11], v[2:3], 0, s[28:29]
	v_lshl_add_u64 v[12:13], v[2:3], 0, s[24:25]
	global_load_dwordx4 v[62:65], v[10:11], off offset:256
	global_load_dwordx4 v[66:69], v[12:13], off offset:256
	v_add_co_u32_e32 v10, vcc, s19, v2
	s_mov_b32 s19, 0x60000
	s_nop 0
	v_addc_co_u32_e32 v11, vcc, 0, v3, vcc
	v_add_co_u32_e32 v2, vcc, s19, v2
	s_movk_i32 s19, 0x2000
	s_nop 0
	v_addc_co_u32_e32 v3, vcc, 0, v3, vcc
	global_load_dwordx4 v[70:73], v[10:11], off
	global_load_dwordx4 v[74:77], v[2:3], off
	v_add_co_u32_e32 v2, vcc, s19, v4
	s_waitcnt lgkmcnt(0)
	v_mfma_f32_32x32x16_bf16 v[18:33], v[6:9], v[58:61], v[18:33]
	v_addc_co_u32_e32 v3, vcc, 0, v5, vcc
	global_load_dwordx4 v[78:81], v[2:3], off
	v_lshlrev_b32_e32 v2, 1, v56
	v_and_b32_e32 v10, 32, v2
	ds_read_b128 v[2:5], v199
	v_and_b32_e32 v6, 0x100, v57
	v_or3_b32 v57, v82, v10, v6
	v_or_b32_e32 v10, 64, v0
	v_mad_u32_u24 v210, v176, s74, v10
	v_add_u32_e32 v211, s18, v210
	ds_read_b128 v[6:9], v211
	s_waitcnt lgkmcnt(1)
	v_mfma_f32_32x32x16_bf16 v[34:49], v[2:5], v[58:61], v[34:49]
	ds_read_b128 v[2:5], v184 offset:64
	v_or_b32_e32 v14, 0x60, v0
	v_add_u32_e32 v212, v10, v55
	v_mad_u32_u24 v214, v176, s74, v14
	v_add_u32_e32 v213, s18, v212
	v_add_u32_e32 v215, s18, v214
	ds_read_b128 v[10:13], v213
	ds_read_b128 v[58:61], v184 offset:96
	s_waitcnt lgkmcnt(2)
	v_mfma_f32_32x32x16_bf16 v[18:33], v[6:9], v[2:5], v[18:33]
	ds_read_b128 v[6:9], v215
	v_add_u32_e32 v216, v14, v55
	v_add_u32_e32 v217, s18, v216
	ds_read_b128 v[82:85], v217
	s_waitcnt vmcnt(0)
	s_waitcnt vmcnt(4)
	ds_write_b128 v185, v[62:65] offset:16384
	s_waitcnt vmcnt(3)
	ds_write_b128 v186, v[66:69] offset:16384
	s_waitcnt vmcnt(2)
	ds_write_b128 v187, v[70:73] offset:50176
	s_waitcnt vmcnt(1)
	ds_write_b128 v187, v[74:77] offset:58880
	s_waitcnt lgkmcnt(7)
	v_mfma_f32_32x32x16_bf16 v[34:49], v[10:13], v[2:5], v[34:49]
	v_add_u32_e32 v182, s17, v57
	s_waitcnt vmcnt(0)
	ds_write_b128 v219, v[78:81]
	s_waitcnt lgkmcnt(0)
	s_barrier
	v_mfma_f32_32x32x16_bf16 v[18:33], v[6:9], v[58:61], v[18:33]
	v_mov_b64_e32 v[2:3], s[76:77]
	v_mov_b64_e32 v[16:17], s[90:91]
	v_mov_b64_e32 v[4:5], s[78:79]
	v_mov_b64_e32 v[6:7], s[80:81]
	v_mov_b64_e32 v[8:9], s[82:83]
	v_mov_b64_e32 v[10:11], s[84:85]
	v_mov_b64_e32 v[12:13], s[86:87]
	v_mfma_f32_32x32x16_bf16 v[34:49], v[82:85], v[58:61], v[34:49]
	s_nop 3
	v_max_f32_e32 v55, v19, v19
	v_max_f32_e32 v58, v18, v18
	v_max_f32_e32 v55, v58, v55
	v_max3_f32 v55, v55, v20, v21
	v_max3_f32 v55, v55, v22, v23
	v_max3_f32 v55, v55, v24, v25
	v_max3_f32 v55, v55, v26, v27
	v_max3_f32 v55, v55, v28, v29
	v_max3_f32 v55, v55, v30, v31
	v_max3_f32 v55, v55, v32, v33
	v_max3_f32 v55, v55, v34, v35
	v_max3_f32 v55, v55, v36, v37
	v_max3_f32 v55, v55, v38, v39
	v_max3_f32 v55, v55, v40, v41
	v_max3_f32 v55, v55, v42, v43
	v_max3_f32 v55, v55, v44, v45
	v_max3_f32 v55, v55, v46, v47
	v_max3_f32 v55, v55, v48, v49
	v_mov_b32_e32 v58, v55
	s_nop 1
	v_permlane32_swap_b32_e32 v55, v58
	v_max_f32_e32 v58, v58, v58
	v_max_f32_e32 v55, v55, v55
	v_max_f32_e32 v55, v55, v58
	v_add_f32_e32 v58, 0x7149f2ca, v55
	v_cmp_ge_f32_e32 vcc, s21, v58
	s_cmp_eq_u64 vcc, exec
	v_max_f32_e32 v54, 0xf149f2ca, v55
	s_cselect_b64 vcc, -1, 0
	v_cndmask_b32_e32 v229, v54, v205, vcc
	v_sub_f32_e32 v55, 0xf149f2ca, v54
	v_mul_f32_e32 v54, 0xbdd53b94, v229
	v_fmamk_f32 v18, v18, 0x3dd53b94, v54
	v_exp_f32_e32 v66, v18
	v_fmamk_f32 v18, v19, 0x3dd53b94, v54
	v_exp_f32_e32 v67, v18
	v_fmamk_f32 v18, v20, 0x3dd53b94, v54
	v_exp_f32_e32 v68, v18
	v_fmamk_f32 v18, v21, 0x3dd53b94, v54
	v_exp_f32_e32 v69, v18
	v_fmamk_f32 v18, v22, 0x3dd53b94, v54
	v_exp_f32_e32 v70, v18
	v_fmamk_f32 v18, v23, 0x3dd53b94, v54
	v_exp_f32_e32 v71, v18
	v_fmamk_f32 v18, v24, 0x3dd53b94, v54
	v_exp_f32_e32 v72, v18
	v_fmamk_f32 v18, v25, 0x3dd53b94, v54
	v_exp_f32_e32 v73, v18
	v_fmamk_f32 v18, v26, 0x3dd53b94, v54
	v_exp_f32_e32 v74, v18
	v_fmamk_f32 v18, v27, 0x3dd53b94, v54
	v_exp_f32_e32 v75, v18
	v_fmamk_f32 v18, v28, 0x3dd53b94, v54
	v_mul_f32_e32 v55, 0x3dd53b94, v55
	v_exp_f32_e32 v76, v18
	v_fmamk_f32 v18, v29, 0x3dd53b94, v54
	v_exp_f32_e32 v55, v55
	v_exp_f32_e32 v77, v18
	v_fmamk_f32 v18, v30, 0x3dd53b94, v54
	v_exp_f32_e32 v78, v18
	v_fmamk_f32 v18, v31, 0x3dd53b94, v54
	v_exp_f32_e32 v79, v18
	v_fmamk_f32 v18, v32, 0x3dd53b94, v54
	v_exp_f32_e32 v80, v18
	v_and_b32_e32 v18, 7, v56
	v_pk_fma_f32 v[96:97], v[48:49], s[36:37], v[54:55] op_sel_hi:[1,0,0]
	v_pk_fma_f32 v[94:95], v[46:47], s[36:37], v[54:55] op_sel_hi:[1,0,0]
	v_pk_fma_f32 v[92:93], v[44:45], s[36:37], v[54:55] op_sel_hi:[1,0,0]
	v_pk_fma_f32 v[90:91], v[42:43], s[36:37], v[54:55] op_sel_hi:[1,0,0]
	v_pk_fma_f32 v[88:89], v[40:41], s[36:37], v[54:55] op_sel_hi:[1,0,0]
	v_pk_fma_f32 v[86:87], v[38:39], s[36:37], v[54:55] op_sel_hi:[1,0,0]
	v_pk_fma_f32 v[84:85], v[36:37], s[36:37], v[54:55] op_sel_hi:[1,0,0]
	v_pk_fma_f32 v[82:83], v[34:35], s[36:37], v[54:55] op_sel_hi:[1,0,0]
	v_fmac_f32_e32 v54, 0x3dd53b94, v33
	v_lshl_or_b32 v168, v18, 4, v168
	v_lshl_add_u64 v[18:19], v[50:51], 0, s[2:3]
	v_exp_f32_e32 v81, v54
	v_lshlrev_b64 v[170:171], 12, v[18:19]
	v_and_b32_e32 v18, 15, v56
	s_addk_i32 s17, 0x4000
	v_lshlrev_b32_e32 v18, 4, v18
	v_mov_b64_e32 v[14:15], s[88:89]
	v_cndmask_b32_e64 v220, v55, 1.0, vcc
	v_add_u32_e32 v181, s17, v57
	v_or3_b32 v170, v170, s20, v18
	v_mov_b64_e32 v[64:65], v[16:17]
	v_mov_b64_e32 v[48:49], v[16:17]
	v_mov_b64_e32 v[32:33], v[16:17]
	v_mov_b64_e32 v[62:63], v[14:15]
	v_mov_b64_e32 v[60:61], v[12:13]
	v_mov_b64_e32 v[58:59], v[10:11]
	v_mov_b64_e32 v[56:57], v[8:9]
	v_mov_b64_e32 v[54:55], v[6:7]
	v_mov_b64_e32 v[52:53], v[4:5]
	v_mov_b64_e32 v[50:51], v[2:3]
	v_mov_b64_e32 v[46:47], v[14:15]
	v_mov_b64_e32 v[44:45], v[12:13]
	v_mov_b64_e32 v[42:43], v[10:11]
	v_mov_b64_e32 v[40:41], v[8:9]
	v_mov_b64_e32 v[38:39], v[6:7]
	v_mov_b64_e32 v[36:37], v[4:5]
	v_mov_b64_e32 v[34:35], v[2:3]
	v_mov_b64_e32 v[30:31], v[14:15]
	v_mov_b64_e32 v[28:29], v[12:13]
	v_mov_b64_e32 v[26:27], v[10:11]
	v_mov_b64_e32 v[24:25], v[8:9]
	v_mov_b64_e32 v[22:23], v[6:7]
	v_mov_b64_e32 v[20:21], v[4:5]
	v_mov_b64_e32 v[18:19], v[2:3]
	s_nop 0

; #define SBAR() __builtin_amdgcn_sched_barrier(0)
; #define SWAIT() do { if constexpr (SD == 1) asm volatile("s_waitcnt vmcnt(0)" ::: "memory"); else asm volatile("s_waitcnt vmcnt(4)" ::: "memory"); } while (0)
; #define RESC(a) do { if (__any((a) < 1.f)) { if (hi == 0) al_l[r32] = (a); asm volatile("s_waitcnt lgkmcnt(0)" ::: "memory"); \
;     _Pragma("unroll") for (int d = 0; d < 4; ++d) _Pragma("unroll") for (int r = 0; r < 16; ++r) o[d][r] *= al_l[crow(r, hi)]; } } while (0)
; __device__ __forceinline__ void finishSM(f32x16& p0, f32x16& p1, float alpha, float& l_reg, bf16x8& pa0, bf16x8& pa1, bf16x8& pa2, bf16x8& pa3) {
;     ...
;   l_reg = l_reg * alpha + ps;
; template <int DQK, int LDK> ...
;     ...
;   for (int j = 1; j + 1 < NT; j += 2) {
;     SBAR(); qkt<DQK>(pB0, pB1, (bf16_t*)((char*)K_lds + SHM_K), KR_lds + SHM_KR, QRw, qr, r32, hi);
;     finishSM(pA0, pA1, alA, l_reg, pa0, pa1, pa2, pa3); SBAR();
;     SLOAD(SO, (j + SD) * KVBLK); SBAR();
;     pv_partialSM<DQK>(o, vb0, pa0, pa1, pa2, pa3, pB0, pB1, m_reg, alB);
;     __syncthreads(); SWAIT(); SWRITE(0, SE);
;     RESC(alB); __syncthreads();
;     SBAR(); qkt<DQK>(pA0, pA1, K_lds, KR_lds, QRw, qr, r32, hi);
;     finishSM(pB0, pB1, alB, l_reg, pa0, pa1, pa2, pa3); SBAR();
;     if (SD == 1 || j + 3 < NT) SLOAD(SE, (j + 1 + SD) * KVBLK); SBAR();
;     pv_partialSM<DQK>(o, vb0 + (int)SHM_V, pa0, pa1, pa2, pa3, pA0, pA1, m_reg, alA);
;     __syncthreads(); SWAIT(); SWRITE(1, SO);
;     RESC(alA); __syncthreads();
.LBB0_351:
	v_add_f32_e32 v98, v230, v231
	s_mov_b64 s[2:3], 0x4000
	v_fmac_f32_e32 v98, v220, v180
	v_add_f32_e32 v180, v234, v235
	v_lshl_add_u64 v[168:169], v[168:169], 0, s[2:3]
	s_add_i32 s16, s16, 2
	s_mov_b64 s[2:3], 0x80000
	v_fmac_f32_e32 v180, v98, v232
	s_cmp_ge_u32 s16, s15
	v_lshl_add_u64 v[170:171], v[170:171], 0, s[2:3]
	s_waitcnt lgkmcnt(0)
	s_barrier
	s_cbranch_scc1 .LBB0_353
	v_mov_b32_e32 v220, v172
	s_branch .LBB0_343
	s_nop 0
